# speedup vs baseline: 1.0447x; 1.0097x over previous
; #define WAIT_V(n) asm volatile("s_waitcnt vmcnt(" #n ")" ::: "memory")
; #define BAR() __builtin_amdgcn_s_barrier()
; #define WAIT_L(n) asm volatile("s_waitcnt lgkmcnt(" #n ")" ::: "memory")
; __device__ __forceinline__ void gemm_phase(const GemmArgs& a, char* smem) {
;     ...
;     if (id == (int)blockIdx.x) {
;       TILE_SETUP(id);
;       WAIT_V(0);
;       WAIT_L(0);
;       BAR();
;       STAGE_B(0, 0, 0); STAGE_A(0, 0, 0);
;       STAGE_B(0, 1, 0); STAGE_A(0, 1, 0);
;     }
.LBB0_197:
	v_readlane_b32 s96, v253, 44
	s_mov_b32 s98, 0
	s_waitcnt vmcnt(0)
	v_readlane_b32 s72, v250, 41
	s_lshl_b32 s96, s6, 8
	s_waitcnt lgkmcnt(0)
	s_barrier
	v_readlane_b32 s73, v250, 42
	s_mov_b32 s2, m0
	s_mov_b32 m0, s31
	s_nop 0
	global_load_lds_dwordx4 v178, s[72:73]
	s_mov_b32 m0, s2
	s_add_u32 s2, s72, s94
	v_mul_lo_u32 v0, v176, s6
	s_addc_u32 s3, s73, 0
	s_mov_b32 s7, m0
	s_mov_b32 m0, s4
	s_nop 0
	global_load_lds_dwordx4 v178, s[2:3]
	s_mov_b32 m0, s7
	s_lshl_b32 s8, s6, 7
	v_add_lshl_u32 v187, v0, v177, 1
	s_mov_b32 s7, m0
	s_mov_b32 m0, s29
	s_nop 0
	global_load_lds_dwordx4 v187, s[88:89]
	s_mov_b32 m0, s7
	s_add_u32 s6, s88, s8
	s_addc_u32 s7, s89, 0
	s_add_u32 s2, s2, s94
	s_mov_b32 s9, m0
	s_mov_b32 m0, s5
	s_nop 0
	global_load_lds_dwordx4 v187, s[6:7]
	s_mov_b32 m0, s9
	s_addc_u32 s3, s3, 0
	s_mov_b32 s9, m0
	s_mov_b32 m0, s0
	s_nop 0
	global_load_lds_dwordx4 v178, s[2:3]
	s_mov_b32 m0, s9
	s_add_u32 s2, s2, s94
	s_addc_u32 s3, s3, 0
	s_mov_b32 s9, m0
	s_mov_b32 m0, s1
	s_nop 0
	global_load_lds_dwordx4 v178, s[2:3]
	s_mov_b32 m0, s9
	s_add_u32 s2, s6, s8
	s_addc_u32 s3, s7, 0
	s_mov_b32 s6, m0
	s_mov_b32 m0, s16
	s_nop 0
	global_load_lds_dwordx4 v187, s[2:3]
	s_mov_b32 m0, s6
	s_add_u32 s2, s2, s8
	v_readlane_b32 s97, v253, 45
	s_addc_u32 s3, s3, 0
	s_mov_b32 s6, m0
	s_mov_b32 m0, s17
	s_nop 0
	global_load_lds_dwordx4 v187, s[2:3]
	s_mov_b32 m0, s6
	s_mov_b32 s3, s97
	v_writelane_b32 v253, s2, 44
	v_readlane_b32 s12, v250, 37
	s_nop 0
	v_writelane_b32 v253, s3, 45
	v_readlane_b32 s2, v250, 40
	s_mov_b32 s56, s2

; #define WAIT_V(n) asm volatile("s_waitcnt vmcnt(" #n ")" ::: "memory")
; #define BAR() __builtin_amdgcn_s_barrier()
; __device__ __forceinline__ void gemm_phase(const GemmArgs& a, char* smem) {
;     ...
;     f32x4 acc[2][2][4][2];
; #pragma unroll
;     for (int i0 = 0; i0 < 2; ++i0)
; #pragma unroll
;       for (int i1 = 0; i1 < 2; ++i1)
; #pragma unroll
;         for (int i2 = 0; i2 < 4; ++i2)
; #pragma unroll
;           for (int i3 = 0; i3 < 2; ++i3) acc[i0][i1][i2][i3] = f32x4{0.f, 0.f, 0.f, 0.f};
;     ...
;     if (wr0 == 1) BAR();
;     WAIT_V(4); BAR();
;     STAGE_B(1, 0, 1); STAGE_A(1, 0, 1); STAGE_B(1, 1, 1);
;     WAIT_V(6); BAR();
.LBB0_200:
	s_or_b64 exec, exec, s[6:7]
	s_add_u32 s2, s72, 0x80
	s_addc_u32 s3, s73, 0
	s_add_u32 s8, s72, s94
	s_addc_u32 s9, s73, 0
	s_cmp_eq_u32 s98, 1
	s_cbranch_scc1 .Lpro_skip4
	s_waitcnt vmcnt(4)
.Lpro_skip4:
	s_barrier
	s_mov_b32 s6, m0
	s_mov_b32 m0, s13
	s_nop 0
	global_load_lds_dwordx4 v178, s[2:3]
	s_mov_b32 m0, s6
	s_add_u32 s2, s8, 0x80
	s_addc_u32 s3, s9, 0
	s_mov_b32 s6, m0
	s_mov_b32 m0, s26
	s_nop 0
	global_load_lds_dwordx4 v178, s[2:3]
	s_mov_b32 m0, s6
	s_add_u32 s2, s88, s42
	s_addc_u32 s3, s89, s43
	s_mov_b32 s6, m0
	s_mov_b32 m0, s27
	s_nop 0
	global_load_lds_dwordx4 v187, s[2:3]
	s_mov_b32 m0, s6
	s_ashr_i64 s[6:7], s[96:97], 1
	s_add_u32 s2, s2, s6
	s_addc_u32 s3, s3, s7
	s_add_u32 s8, s8, s94
	s_addc_u32 s9, s9, 0
	s_mov_b32 s10, m0
	s_mov_b32 m0, s24
	s_nop 0
	global_load_lds_dwordx4 v187, s[2:3]
	s_mov_b32 m0, s10
	s_add_u32 s2, s8, 0x80
	s_addc_u32 s3, s9, 0
	s_mov_b32 s10, m0
	s_mov_b32 m0, s25
	s_nop 0
	global_load_lds_dwordx4 v178, s[2:3]
	s_mov_b32 m0, s10
	s_add_u32 s2, s8, s94
	s_addc_u32 s3, s9, 0
	s_add_u32 s2, s2, 0x80
	s_addc_u32 s3, s3, 0
	s_mov_b32 s8, m0
	s_mov_b32 m0, s34
	s_nop 0
	global_load_lds_dwordx4 v178, s[2:3]
	s_mov_b32 m0, s8
	s_mul_i32 s2, s43, 3
	s_mul_hi_u32 s3, s42, 3
	s_add_i32 s12, s3, s2
	s_mul_i32 s15, s42, 3
	s_add_u32 s57, s6, s15
	s_addc_u32 s90, s7, s12
	s_lshl_b64 s[8:9], s[42:43], 1
	s_add_u32 s22, s96, s8
	s_addc_u32 s23, s97, s9
	s_add_u32 s2, s22, s6
	s_addc_u32 s3, s23, s7
	s_add_u32 s37, s6, s8
	s_addc_u32 s44, s7, s9
	s_add_u32 s45, s42, s96
	s_addc_u32 s19, s43, s97
	s_cmp_eq_u32 s98, 1
	s_cbranch_scc1 .Lpro_skip6
	s_waitcnt vmcnt(6)
.Lpro_skip6:
	s_mov_b32 s98, 0
	s_add_u32 s38, s45, s6
	v_mov_b32_e32 v0, 0
	v_readlane_b32 s68, v250, 49
	v_readlane_b32 s50, v250, 46
	s_addc_u32 s74, s19, s7
	s_mov_b32 s75, 0
	s_mov_b64 s[10:11], 0
	s_mov_b64 s[62:63], s[8:9]
	s_mov_b64 vcc, s[94:95]
	v_readlane_b32 s69, v250, 50
	v_readlane_b32 s51, v250, 47
	s_waitcnt lgkmcnt(0)
	v_mov_b32_e32 v1, v0
	v_mov_b32_e32 v2, v0
	v_mov_b32_e32 v3, v0
	v_mov_b32_e32 v4, v0
	v_mov_b32_e32 v5, v0
	v_mov_b32_e32 v6, v0
	v_mov_b32_e32 v7, v0
	v_mov_b32_e32 v8, v0
	v_mov_b32_e32 v9, v0
	v_mov_b32_e32 v10, v0
	v_mov_b32_e32 v11, v0
	v_mov_b32_e32 v12, v0
	v_mov_b32_e32 v13, v0
	v_mov_b32_e32 v14, v0
	v_mov_b32_e32 v15, v0
	v_mov_b32_e32 v16, v0
	v_mov_b32_e32 v17, v0
	v_mov_b32_e32 v18, v0
	v_mov_b32_e32 v19, v0
	v_mov_b32_e32 v20, v0
	v_mov_b32_e32 v21, v0
	v_mov_b32_e32 v22, v0
	v_mov_b32_e32 v23, v0
	v_mov_b32_e32 v24, v0
	v_mov_b32_e32 v25, v0
	v_mov_b32_e32 v26, v0
	v_mov_b32_e32 v27, v0
	v_mov_b32_e32 v28, v0
	v_mov_b32_e32 v29, v0
	v_mov_b32_e32 v30, v0
	v_mov_b32_e32 v31, v0
	v_mov_b32_e32 v76, v0
	v_mov_b32_e32 v77, v0
	v_mov_b32_e32 v78, v0
	v_mov_b32_e32 v79, v0
	v_mov_b32_e32 v92, v0
	v_mov_b32_e32 v93, v0
	v_mov_b32_e32 v94, v0
	v_mov_b32_e32 v95, v0
	v_mov_b32_e32 v104, v0
	v_mov_b32_e32 v105, v0
	v_mov_b32_e32 v106, v0
	v_mov_b32_e32 v107, v0
	v_mov_b32_e32 v108, v0
	v_mov_b32_e32 v109, v0
	v_mov_b32_e32 v110, v0
	v_mov_b32_e32 v111, v0
	v_mov_b32_e32 v112, v0
	v_mov_b32_e32 v113, v0
	v_mov_b32_e32 v114, v0
	v_mov_b32_e32 v115, v0
	v_mov_b32_e32 v116, v0
	v_mov_b32_e32 v117, v0
	v_mov_b32_e32 v118, v0
	v_mov_b32_e32 v119, v0
	v_mov_b32_e32 v120, v0
	v_mov_b32_e32 v121, v0
	v_mov_b32_e32 v122, v0
	v_mov_b32_e32 v123, v0
	v_mov_b32_e32 v124, v0
	v_mov_b32_e32 v125, v0
	v_mov_b32_e32 v126, v0
	v_mov_b32_e32 v127, v0
	v_mov_b32_e32 v32, v0
	v_mov_b32_e32 v33, v0
	v_mov_b32_e32 v34, v0
	v_mov_b32_e32 v35, v0
	v_mov_b32_e32 v36, v0
	v_mov_b32_e32 v37, v0
	v_mov_b32_e32 v38, v0
	v_mov_b32_e32 v39, v0
	v_mov_b32_e32 v40, v0
	v_mov_b32_e32 v41, v0
	v_mov_b32_e32 v42, v0
	v_mov_b32_e32 v43, v0
	v_mov_b32_e32 v44, v0
	v_mov_b32_e32 v45, v0
	v_mov_b32_e32 v46, v0
	v_mov_b32_e32 v47, v0
	v_mov_b32_e32 v48, v0
	v_mov_b32_e32 v49, v0
	v_mov_b32_e32 v50, v0
	v_mov_b32_e32 v51, v0
	v_mov_b32_e32 v52, v0
	v_mov_b32_e32 v53, v0
	v_mov_b32_e32 v54, v0
	v_mov_b32_e32 v55, v0
	v_mov_b32_e32 v60, v0
	v_mov_b32_e32 v61, v0
	v_mov_b32_e32 v62, v0
	v_mov_b32_e32 v63, v0
	v_mov_b32_e32 v68, v0
	v_mov_b32_e32 v69, v0
	v_mov_b32_e32 v70, v0
	v_mov_b32_e32 v71, v0
	v_mov_b32_e32 v56, v0
	v_mov_b32_e32 v57, v0
	v_mov_b32_e32 v58, v0
	v_mov_b32_e32 v59, v0
	v_mov_b32_e32 v64, v0
	v_mov_b32_e32 v65, v0
	v_mov_b32_e32 v66, v0
	v_mov_b32_e32 v67, v0
	v_mov_b32_e32 v72, v0
	v_mov_b32_e32 v73, v0
	v_mov_b32_e32 v74, v0
	v_mov_b32_e32 v75, v0
	v_mov_b32_e32 v80, v0
	v_mov_b32_e32 v81, v0
	v_mov_b32_e32 v82, v0
	v_mov_b32_e32 v83, v0
	v_mov_b32_e32 v84, v0
	v_mov_b32_e32 v85, v0
	v_mov_b32_e32 v86, v0
	v_mov_b32_e32 v87, v0
	v_mov_b32_e32 v88, v0
	v_mov_b32_e32 v89, v0
	v_mov_b32_e32 v90, v0
	v_mov_b32_e32 v91, v0
	v_mov_b32_e32 v96, v0
	v_mov_b32_e32 v97, v0
	v_mov_b32_e32 v98, v0
	v_mov_b32_e32 v99, v0
	v_mov_b32_e32 v100, v0
	v_mov_b32_e32 v101, v0
	v_mov_b32_e32 v102, v0
	v_mov_b32_e32 v103, v0
	s_barrier

;   __device__ __forceinline__ float* ss() const { return (float*)(ws + OFF_ss); }
;   __device__ __forceinline__ bf16* z() const { return (bf16*)(ws + OFF_z); }
; __device__ __forceinline__ void gemm_phase(const GemmArgs& a, char* smem) {
;     ...
;     float rr[2][4];
;     if (emode <= 1) {
; #pragma unroll
;       for (int ai = 0; ai < 2; ++ai)
; #pragma unroll
;         for (int m = 0; m < 4; ++m) {
;           const int row = brow + ai * 128 + wr * 64 + m * 16 + fr;
;           const float4 sq = *(const float4*)(a.ss + (long)row * 4);
;           rr[ai][m] = rsqrtf(((sq.x + sq.y) + (sq.z + sq.w)) * (1.0f / 1024.0f) + EPS);
;         }
;     }
.LBB0_214:
	v_mov_b32_e32 v192, v155
	v_readlane_b32 s2, v250, 5
	v_readlane_b32 s3, v250, 6
	v_ashrrev_i32_e32 v193, 6, v192
	v_ashrrev_i32_e32 v191, 8, v192
	v_and_b32_e32 v190, 3, v193
	v_and_b32_e32 v188, 15, v192
	v_bfe_u32 v189, v192, 4, 2
	s_mov_b64 s[6:7], -1
	s_and_b64 vcc, exec, s[2:3]
	s_cbranch_vccz .LBB0_300
	v_readlane_b32 s2, v251, 43
	v_readlane_b32 s3, v251, 44
	v_lshlrev_b32_e32 v128, 6, v191
	s_andn2_b64 vcc, exec, s[2:3]
	v_add3_u32 v158, v188, s22, v128
	v_mov_b64_e32 v[164:165], v[144:145]
	v_mov_b64_e32 v[162:163], v[146:147]
	v_mov_b64_e32 v[160:161], v[148:149]
	v_mov_b64_e32 v[156:157], v[150:151]
	s_cbranch_vccnz .LBB0_217
	v_readlane_b32 s10, v251, 57
	v_readlane_b32 s11, v251, 58
	v_ashrrev_i32_e32 v159, 31, v158
	s_mov_b32 s2, 0x3a800000
	s_mov_b32 s8, 0x45800000
	v_lshlrev_b32_e32 v128, 4, v158
	v_mov_b32_e32 v148, 0x358637bd
	s_nop 1
	global_load_dwordx4 v[132:135], v128, s[10:11] offset:256
	global_load_dwordx4 v[198:201], v128, s[10:11] offset:512
	global_load_dwordx4 v[202:205], v128, s[10:11] offset:768
	global_load_dwordx4 v[206:209], v128, s[10:11] offset:2048
	global_load_dwordx4 v[218:221], v128, s[10:11] offset:2304
	global_load_dwordx4 v[222:225], v128, s[10:11] offset:2560
	global_load_dwordx4 v[140:143], v128, s[10:11] offset:2816
	s_nop 0
	global_load_dwordx4 v[128:131], v128, s[10:11]
	s_waitcnt vmcnt(0)
	v_add_f32_e32 v144, v132, v133
	v_add_f32_e32 v145, v128, v129
	v_add_f32_e32 v146, v134, v135
	v_add_f32_e32 v147, v130, v131
	v_add_f32_e32 v144, v144, v146
	v_add_f32_e32 v145, v145, v147
	v_fma_f32 v144, v144, s2, v148
	v_fma_f32 v145, v145, s2, v148
	v_cmp_gt_f32_e32 vcc, s71, v144
	v_cmp_gt_f32_e64 s[6:7], s71, v145
	v_mul_f32_e32 v146, 0x4b800000, v144
	v_mul_f32_e32 v147, 0x4b800000, v145
	v_cndmask_b32_e32 v144, v144, v146, vcc
	v_cndmask_b32_e64 v145, v145, v147, s[6:7]
	v_rsq_f32_e32 v144, v144
	v_rsq_f32_e32 v145, v145
	s_nop 0
	v_mul_f32_e32 v146, s8, v144
	v_mul_f32_e32 v147, s8, v145
	v_cndmask_b32_e32 v156, v144, v146, vcc
	v_cndmask_b32_e64 v157, v145, v147, s[6:7]
	v_add_f32_e32 v144, v202, v203
	v_add_f32_e32 v145, v198, v199
	v_add_f32_e32 v146, v204, v205
	v_add_f32_e32 v147, v200, v201
	v_add_f32_e32 v144, v144, v146
	v_add_f32_e32 v145, v145, v147
	v_fma_f32 v144, v144, s2, v148
	v_fma_f32 v145, v145, s2, v148
	v_cmp_gt_f32_e32 vcc, s71, v144
	v_cmp_gt_f32_e64 s[6:7], s71, v145
	v_mul_f32_e32 v146, 0x4b800000, v144
	v_mul_f32_e32 v147, 0x4b800000, v145
	v_cndmask_b32_e32 v144, v144, v146, vcc
	v_cndmask_b32_e64 v145, v145, v147, s[6:7]
	v_rsq_f32_e32 v144, v144
	v_rsq_f32_e32 v145, v145
	s_nop 0
	v_mul_f32_e32 v146, s8, v144
	v_mul_f32_e32 v147, s8, v145
	v_cndmask_b32_e32 v160, v144, v146, vcc
	v_cndmask_b32_e64 v161, v145, v147, s[6:7]
	v_add_f32_e32 v144, v218, v219
	v_add_f32_e32 v145, v206, v207
	v_add_f32_e32 v146, v220, v221
	v_add_f32_e32 v147, v208, v209
	v_add_f32_e32 v144, v144, v146
	v_add_f32_e32 v145, v145, v147
	v_fma_f32 v144, v144, s2, v148
	v_fma_f32 v145, v145, s2, v148
	v_cmp_gt_f32_e32 vcc, s71, v144
	v_cmp_gt_f32_e64 s[6:7], s71, v145
	v_mul_f32_e32 v146, 0x4b800000, v144
	v_mul_f32_e32 v147, 0x4b800000, v145
	v_cndmask_b32_e32 v144, v144, v146, vcc
	v_cndmask_b32_e64 v145, v145, v147, s[6:7]
	v_rsq_f32_e32 v144, v144
	v_rsq_f32_e32 v145, v145
	s_nop 0
	v_mul_f32_e32 v146, s8, v144
	v_mul_f32_e32 v147, s8, v145
	v_cndmask_b32_e32 v162, v144, v146, vcc
	v_cndmask_b32_e64 v163, v145, v147, s[6:7]
	v_add_f32_e32 v144, v140, v141
	v_add_f32_e32 v145, v222, v223
	v_add_f32_e32 v146, v142, v143
	v_add_f32_e32 v147, v224, v225
	v_add_f32_e32 v144, v144, v146
	v_add_f32_e32 v145, v145, v147
	v_fma_f32 v144, v144, s2, v148
	v_fma_f32 v145, v145, s2, v148
	v_cmp_gt_f32_e32 vcc, s71, v144
	v_cmp_gt_f32_e64 s[6:7], s71, v145
	v_mul_f32_e32 v146, 0x4b800000, v144
	v_mul_f32_e32 v147, 0x4b800000, v145
	v_cndmask_b32_e32 v144, v144, v146, vcc
	v_cndmask_b32_e64 v145, v145, v147, s[6:7]
	v_rsq_f32_e32 v144, v144
	v_rsq_f32_e32 v145, v145
	s_nop 0
	v_mul_f32_e32 v146, s8, v144
	v_mul_f32_e32 v147, s8, v145
	v_cndmask_b32_e32 v164, v144, v146, vcc
	v_cndmask_b32_e64 v165, v145, v147, s[6:7]
	s_andn2_b64 vcc, exec, s[62:63]
	s_cselect_b32 s98, 1, 0

; __global__ void __launch_bounds__(512, 2) mega_kernel(Params p) {
;   __shared__ __attribute__((aligned(16))) char smem[131072];
	.amdhsa_kernel _Z11mega_kernel6Params
		.amdhsa_group_segment_fixed_size 131072
		.amdhsa_private_segment_fixed_size 0
		.amdhsa_kernarg_size 448
		.amdhsa_user_sgpr_count 2
		.amdhsa_user_sgpr_dispatch_ptr 0
		.amdhsa_user_sgpr_queue_ptr 0
		.amdhsa_user_sgpr_kernarg_segment_ptr 1
		.amdhsa_user_sgpr_dispatch_id 0
		.amdhsa_user_sgpr_kernarg_preload_length 0
		.amdhsa_user_sgpr_kernarg_preload_offset 0
		.amdhsa_user_sgpr_private_segment_size 0
		.amdhsa_uses_dynamic_stack 0
		.amdhsa_enable_private_segment 0
		.amdhsa_system_sgpr_workgroup_id_x 1
		.amdhsa_system_sgpr_workgroup_id_y 0
		.amdhsa_system_sgpr_workgroup_id_z 0
		.amdhsa_system_sgpr_workgroup_info 0
		.amdhsa_system_vgpr_workitem_id 2
		.amdhsa_next_free_vgpr 254
		.amdhsa_next_free_sgpr 100
		.amdhsa_accum_offset 256
		.amdhsa_reserve_vcc 1
		.amdhsa_float_round_mode_32 0
		.amdhsa_float_round_mode_16_64 0
		.amdhsa_float_denorm_mode_32 3
		.amdhsa_float_denorm_mode_16_64 3
		.amdhsa_dx10_clamp 1
		.amdhsa_ieee_mode 1
		.amdhsa_fp16_overflow 0
		.amdhsa_tg_split 0
		.amdhsa_exception_fp_ieee_invalid_op 0
		.amdhsa_exception_fp_denorm_src 0
		.amdhsa_exception_fp_ieee_div_zero 0
		.amdhsa_exception_fp_ieee_overflow 0
		.amdhsa_exception_fp_ieee_underflow 0
		.amdhsa_exception_fp_ieee_inexact 0
		.amdhsa_exception_int_div_zero 0
	.end_amdhsa_kernel

; __global__ void __launch_bounds__(512, 2) mega_kernel(Params p) {
;   __shared__ __attribute__((aligned(16))) char smem[131072];
amdhsa.kernels:
  - .agpr_count:     0
    .args:
      - .offset:         0
        .size:           192
        .value_kind:     by_value
      - .offset:         192
        .size:           4
        .value_kind:     hidden_block_count_x
      - .offset:         196
        .size:           4
        .value_kind:     hidden_block_count_y
      - .offset:         200
        .size:           4
        .value_kind:     hidden_block_count_z
      - .offset:         204
        .size:           2
        .value_kind:     hidden_group_size_x
      - .offset:         206
        .size:           2
        .value_kind:     hidden_group_size_y
      - .offset:         208
        .size:           2
        .value_kind:     hidden_group_size_z
      - .offset:         210
        .size:           2
        .value_kind:     hidden_remainder_x
      - .offset:         212
        .size:           2
        .value_kind:     hidden_remainder_y
      - .offset:         214
        .size:           2
        .value_kind:     hidden_remainder_z
      - .offset:         232
        .size:           8
        .value_kind:     hidden_global_offset_x
      - .offset:         240
        .size:           8
        .value_kind:     hidden_global_offset_y
      - .offset:         248
        .size:           8
        .value_kind:     hidden_global_offset_z
      - .offset:         256
        .size:           2
        .value_kind:     hidden_grid_dims
      - .offset:         280
        .size:           8
        .value_kind:     hidden_multigrid_sync_arg
    .group_segment_fixed_size: 131072
    .kernarg_segment_align: 8
    .kernarg_segment_size: 448
    .language:       OpenCL C
    .language_version:
      - 2
      - 0
    .max_flat_workgroup_size: 512
    .name:           _Z11mega_kernel6Params
    .private_segment_fixed_size: 0
    .sgpr_count:     106
    .sgpr_spill_count: 377
    .symbol:         _Z11mega_kernel6Params.kd
    .uniform_work_group_size: 1
    .uses_dynamic_stack: false
    .vgpr_count:     254
    .vgpr_spill_count: 0
    .wavefront_size: 64
